# grid barrier release side rewritten: all blocks wait on the top-level arrival counter reaching (k+1)*nx; no top-generation / per-XCD generation hops
# baseline (speedup 1.0000x reference)
; #define LAS __attribute__((address_space(3)))
; __device__ __forceinline__ unsigned xb_add(unsigned* p, unsigned v) { return __hip_atomic_fetch_add(p, v, __ATOMIC_RELAXED, __HIP_MEMORY_SCOPE_AGENT); }
; __device__ __forceinline__ unsigned xb_xcc_id() { return (unsigned)__builtin_amdgcn_s_getreg((3 << 11) | 20) & 0xFu; }
; __device__ __forceinline__ XcdBarrier xcd_barrier_post(unsigned* bar, volatile LAS unsigned* st) {
;   XcdBarrier b; b.bar = bar; b.x = xb_xcc_id(); b.st = st;
;   if (threadIdx.x == 0) (void)xb_add(&bar[XB_XCNT(b.x)], 1u);
;   return b;
; __global__ void __launch_bounds__(256, 2) k_mega(Params p) {
;   __shared__ __attribute__((aligned(16))) char smem[74240];
;   __shared__ uint4 xb_words;
;   cg::grid_group grid = cg::this_grid();
;   if (threadIdx.x == 0) xb_words = make_uint4(0u, 0u, 0u, 0u);
;   __syncthreads();
;   XcdBarrier xb = xcd_barrier_post(p.bar, (volatile LAS unsigned*)&xb_words);
_Z6k_mega6Params:
	v_writelane_b32 v240, 0, 48
	s_load_dwordx2 s[4:5], s[0:1], 0x118
	s_add_u32 s42, s0, 0x118
	v_writelane_b32 v242, s0, 0
	s_addc_u32 s43, s1, 0
	v_mov_b32_e32 v2, 0
	v_writelane_b32 v242, s1, 1
	v_writelane_b32 v242, s2, 2
	s_waitcnt lgkmcnt(0)
	v_writelane_b32 v242, s4, 3
	s_cmp_lt_u32 s2, s4
	s_cselect_b32 s2, 12, 18
	s_add_u32 s2, s42, s2
	s_addc_u32 s3, s43, 0
	global_load_ushort v1, v2, s[2:3]
	v_and_b32_e32 v156, 0x3ff, v0
	v_writelane_b32 v242, s5, 4
	v_cmp_eq_u32_e64 s[0:1], 0, v156
	s_waitcnt vmcnt(0)
	v_readfirstlane_b32 s6, v1
	v_writelane_b32 v242, s0, 5
	s_nop 1
	v_writelane_b32 v242, s1, 6
	s_and_saveexec_b64 s[2:3], s[0:1]
	v_mov_b32_e32 v3, v2
	v_mov_b32_e32 v4, v2
	v_mov_b32_e32 v5, v2
	v_mov_b32_e32 v1, 0x12200
	ds_write_b128 v1, v[2:5]
	s_or_b64 exec, exec, s[2:3]
	v_readlane_b32 s0, v242, 0
	v_readlane_b32 s1, v242, 1
	s_load_dwordx2 s[0:1], s[0:1], 0x100
	s_waitcnt lgkmcnt(0)
	s_barrier
	s_getreg_b32 s2, hwreg(HW_REG_XCC_ID, 0, 4)
	v_writelane_b32 v242, s0, 7
	s_and_b32 s26, s2, 15
	s_nop 0
	v_writelane_b32 v242, s1, 8
	s_nop 0
	v_readlane_b32 s0, v242, 5
	v_readlane_b32 s1, v242, 6
	s_and_saveexec_b64 s[2:3], s[0:1]
	s_cbranch_execz .LBB0_5
	s_mov_b64 s[4:5], exec
	v_mbcnt_lo_u32_b32 v1, s4, 0
	v_mbcnt_hi_u32_b32 v1, s5, v1
	v_cmp_eq_u32_e32 vcc, 0, v1
	s_and_b64 s[8:9], exec, vcc
	s_mov_b64 exec, s[8:9]
	s_cbranch_execz .LBB0_5
	s_lshl_b32 s7, s26, 8
	s_bcnt1_i32_b64 s4, s[4:5]
	v_readlane_b32 s0, v242, 7
	v_mov_b32_e32 v1, s7
	v_mov_b32_e32 v2, s4
	v_readlane_b32 s1, v242, 8
	s_nop 4
	global_atomic_add v1, v2, s[0:1] offset:1024

; __device__ __forceinline__ unsigned xb_ld(unsigned* p) { return __hip_atomic_load(p, __ATOMIC_RELAXED, __HIP_MEMORY_SCOPE_AGENT); }
; __device__ __forceinline__ unsigned xb_add(unsigned* p, unsigned v) { return __hip_atomic_fetch_add(p, v, __ATOMIC_RELAXED, __HIP_MEMORY_SCOPE_AGENT); }
; #define XB_SPIN(cond, bar) do { unsigned _sp = 0; while (cond) { __builtin_amdgcn_s_sleep(1); \
;     if ((++_sp & 255u) == 0u) { if (xb_ld(&(bar)[XB_TMO])) break; if (_sp > XB_SPIN_CAP) { atomicAdd(&(bar)[XB_TMO], 1u); break; } } } } while (0)
; __device__ __forceinline__ void xcd_barrier(const XcdBarrier& b) {
;   asm volatile("s_waitcnt vmcnt(0)" ::: "memory");
;   __syncthreads();
;   if (threadIdx.x == 0) {
;     unsigned* bar = b.bar;
;     __builtin_amdgcn_s_waitcnt(0);
;     unsigned nloc = b.st[0], nx = b.st[1];
;     if (nloc == 0u) { xcd_barrier_complete(bar, b.x, nloc, nx); b.st[0] = nloc; b.st[1] = nx; }
;     const unsigned old = xb_add(&bar[XB_XSUB(b.x)], 1u);
;     const unsigned gen = old / nloc;
;     if (old + 1u == (gen + 1u) * nloc) {
;       __builtin_amdgcn_fence(__ATOMIC_RELEASE, "agent");
;       asm volatile("s_waitcnt vmcnt(0)" ::: "memory");
;       const unsigned og = xb_add(&bar[XB_TOP], 1u);
;       const unsigned tg = og / nx;
;       if (og + 1u == (tg + 1u) * nx) xb_add(&bar[XB_TOPGEN], 1u);
;       else XB_SPIN(xb_ld(&bar[XB_TOPGEN]) == tg, bar);
;       __builtin_amdgcn_fence(__ATOMIC_ACQUIRE, "agent");
;       xb_add(&bar[XB_XGEN(b.x)], 1u);
;       asm volatile("s_waitcnt vmcnt(0)" ::: "memory");
;     } else {
;       XB_SPIN(xb_ld(&bar[XB_XGEN(b.x)]) == gen, bar);
;       __builtin_amdgcn_fence(__ATOMIC_ACQUIRE, "agent");
;       asm volatile("s_waitcnt vmcnt(0)" ::: "memory");
;     }
;   }
;   __syncthreads();
; }
.LBB0_75:
	s_waitcnt lgkmcnt(0)
	v_readlane_b32 s40, v242, 58
	v_readlane_b32 s41, v242, 59
	v_mov_b32_e32 v4, 1
	v_readlane_b32 s44, v240, 48
	s_add_i32 s44, s44, 1
	v_mul_lo_u32 v6, v3, s44
	v_mul_lo_u32 v5, v2, s44
	s_nop 1
	global_atomic_add v4, v1, v4, s[40:41] sc0
	v_readlane_b32 s42, v242, 62
	v_readlane_b32 s43, v242, 63
	s_waitcnt vmcnt(0)
	v_add_u32_e32 v4, 1, v4
	v_cmp_eq_u32_e32 vcc, v4, v6
	s_cbranch_vccz .Lgb0_poll
	buffer_wbl2 sc1
	s_waitcnt vmcnt(0) lgkmcnt(0)
	v_mov_b32_e32 v4, 1
	global_atomic_add v1, v4, s[42:43]
.Lgb0_poll:
	s_movk_i32 s44, 0x2000
.Lgb0_spin:
	global_load_dword v4, v1, s[42:43] sc1
	s_waitcnt vmcnt(0)
	v_cmp_ge_u32_e32 vcc, v4, v5
	s_cbranch_vccnz .Lgb0_done
	s_sleep 1
	s_sub_u32 s44, s44, 1
	s_cmp_lg_u32 s44, 0
	s_cbranch_scc1 .Lgb0_spin
.Lgb0_done:
	buffer_inv sc1
	s_waitcnt vmcnt(0)
.LBB0_111:
	s_or_b64 exec, exec, s[38:39]
	v_readlane_b32 s98, v240, 48
	s_add_i32 s98, s98, 1
	s_nop 0
	v_writelane_b32 v240, s98, 48
	s_xor_b64 s[12:13], s[14:15], -1
	v_writelane_b32 v240, s12, 22
	v_readlane_b32 s10, v241, 59
	s_mul_i32 s92, s10, 0x6c00
	v_writelane_b32 v240, s13, 23
	s_lshl_b32 s12, s10, 10
	s_mov_b32 s13, s93
	v_writelane_b32 v240, s12, 24
	s_lshl_b64 s[38:39], s[12:13], 2
	s_mov_b64 s[44:45], s[14:15]
	v_writelane_b32 v240, s13, 25
	s_mov_b32 s59, 0x38e38e39
	v_readlane_b32 s12, v240, 4
	v_readlane_b32 s13, v240, 5
	s_add_u32 s12, s12, s38
	s_addc_u32 s13, s13, s39
	v_writelane_b32 v240, s12, 26
	s_lshl_b64 s[40:41], s[92:93], 2
	s_waitcnt lgkmcnt(0)
	v_writelane_b32 v240, s13, 27
	v_readlane_b32 s12, v241, 5
	v_readlane_b32 s13, v241, 6
	s_add_u32 s12, s12, s40
	s_addc_u32 s13, s13, s41
	v_writelane_b32 v240, s12, 28
	v_readlane_b32 s15, v241, 8
	s_mov_b32 s15, 0
	v_writelane_b32 v240, s13, 29
	s_lshl_b32 s12, s10, 3
	v_writelane_b32 v240, s12, 30
	s_lshl_b32 s12, s10, 4
	v_writelane_b32 v240, s12, 31
	s_lshl_b32 s12, s10, 8
	s_and_b64 s[40:41], s[44:45], exec
	v_writelane_b32 v240, s12, 32
	s_cselect_b32 s12, 16, 0xf8
	s_mov_b32 s13, s15
	v_writelane_b32 v240, s12, 33
	v_readlane_b32 s14, v241, 7
	v_readlane_b32 s40, v241, 9
	v_writelane_b32 v240, s13, 34
	s_mul_i32 s12, s10, 17
	s_mov_b32 s13, s93
	v_writelane_b32 v240, s12, 35
	s_cselect_b32 s14, 0, 0xa0
	v_readlane_b32 s41, v241, 10
	v_writelane_b32 v240, s13, 36
	s_add_u32 s12, s40, s38
	s_addc_u32 s13, s41, s39
	v_writelane_b32 v240, s12, 37
	s_barrier
	s_nop 0
	v_writelane_b32 v240, s13, 38
	v_readlane_b32 s12, v241, 60
	v_writelane_b32 v240, s44, 39
	s_and_b64 s[38:39], s[44:45], exec
	v_readlane_b32 s13, v241, 61
	v_writelane_b32 v240, s45, 40
	s_cselect_b32 s13, s13, s77
	s_cselect_b32 s12, s12, s76
	v_writelane_b32 v240, s12, 41
	v_readlane_b32 s42, v241, 11
	v_readlane_b32 s43, v241, 12
	v_writelane_b32 v240, s13, 42
	v_writelane_b32 v240, s14, 43
	s_mov_b32 s64, s15
	s_nop 0
	v_writelane_b32 v240, s15, 44
	s_movk_i32 s14, 0x3000
	s_branch .LBB0_114

; __device__ __forceinline__ unsigned xb_ld(unsigned* p) { return __hip_atomic_load(p, __ATOMIC_RELAXED, __HIP_MEMORY_SCOPE_AGENT); }
; __device__ __forceinline__ unsigned xb_add(unsigned* p, unsigned v) { return __hip_atomic_fetch_add(p, v, __ATOMIC_RELAXED, __HIP_MEMORY_SCOPE_AGENT); }
; #define XB_SPIN(cond, bar) do { unsigned _sp = 0; while (cond) { __builtin_amdgcn_s_sleep(1); \
;     if ((++_sp & 255u) == 0u) { if (xb_ld(&(bar)[XB_TMO])) break; if (_sp > XB_SPIN_CAP) { atomicAdd(&(bar)[XB_TMO], 1u); break; } } } } while (0)
; __device__ __forceinline__ void xcd_barrier(const XcdBarrier& b) {
;   asm volatile("s_waitcnt vmcnt(0)" ::: "memory");
;   __syncthreads();
;   if (threadIdx.x == 0) {
;     unsigned* bar = b.bar;
;     __builtin_amdgcn_s_waitcnt(0);
;     unsigned nloc = b.st[0], nx = b.st[1];
;     if (nloc == 0u) { xcd_barrier_complete(bar, b.x, nloc, nx); b.st[0] = nloc; b.st[1] = nx; }
;     const unsigned old = xb_add(&bar[XB_XSUB(b.x)], 1u);
;     const unsigned gen = old / nloc;
;     if (old + 1u == (gen + 1u) * nloc) {
;       __builtin_amdgcn_fence(__ATOMIC_RELEASE, "agent");
;       asm volatile("s_waitcnt vmcnt(0)" ::: "memory");
;       const unsigned og = xb_add(&bar[XB_TOP], 1u);
;       const unsigned tg = og / nx;
;       if (og + 1u == (tg + 1u) * nx) xb_add(&bar[XB_TOPGEN], 1u);
;       else XB_SPIN(xb_ld(&bar[XB_TOPGEN]) == tg, bar);
;       __builtin_amdgcn_fence(__ATOMIC_ACQUIRE, "agent");
;       xb_add(&bar[XB_XGEN(b.x)], 1u);
;       asm volatile("s_waitcnt vmcnt(0)" ::: "memory");
;     } else {
;       XB_SPIN(xb_ld(&bar[XB_XGEN(b.x)]) == gen, bar);
;       __builtin_amdgcn_fence(__ATOMIC_ACQUIRE, "agent");
;       asm volatile("s_waitcnt vmcnt(0)" ::: "memory");
;     }
;   }
;   __syncthreads();
; }
.LBB0_113:
	s_or_b64 exec, exec, s[38:39]
	v_readlane_b32 s98, v240, 48
	s_add_i32 s98, s98, 1
	s_nop 0
	v_writelane_b32 v240, s98, 48
	s_cmp_eq_u32 s64, 4
	s_waitcnt lgkmcnt(0)
	s_barrier
	s_cbranch_scc1 .LBB0_34

; __device__ __forceinline__ unsigned xb_ld(unsigned* p) { return __hip_atomic_load(p, __ATOMIC_RELAXED, __HIP_MEMORY_SCOPE_AGENT); }
; __device__ __forceinline__ unsigned xb_add(unsigned* p, unsigned v) { return __hip_atomic_fetch_add(p, v, __ATOMIC_RELAXED, __HIP_MEMORY_SCOPE_AGENT); }
; #define XB_SPIN(cond, bar) do { unsigned _sp = 0; while (cond) { __builtin_amdgcn_s_sleep(1); \
;     if ((++_sp & 255u) == 0u) { if (xb_ld(&(bar)[XB_TMO])) break; if (_sp > XB_SPIN_CAP) { atomicAdd(&(bar)[XB_TMO], 1u); break; } } } } while (0)
; __device__ __forceinline__ void xcd_barrier(const XcdBarrier& b) {
;   asm volatile("s_waitcnt vmcnt(0)" ::: "memory");
;   __syncthreads();
;   if (threadIdx.x == 0) {
;     unsigned* bar = b.bar;
;     __builtin_amdgcn_s_waitcnt(0);
;     unsigned nloc = b.st[0], nx = b.st[1];
;     if (nloc == 0u) { xcd_barrier_complete(bar, b.x, nloc, nx); b.st[0] = nloc; b.st[1] = nx; }
;     const unsigned old = xb_add(&bar[XB_XSUB(b.x)], 1u);
;     const unsigned gen = old / nloc;
;     if (old + 1u == (gen + 1u) * nloc) {
;       __builtin_amdgcn_fence(__ATOMIC_RELEASE, "agent");
;       asm volatile("s_waitcnt vmcnt(0)" ::: "memory");
;       const unsigned og = xb_add(&bar[XB_TOP], 1u);
;       const unsigned tg = og / nx;
;       if (og + 1u == (tg + 1u) * nx) xb_add(&bar[XB_TOPGEN], 1u);
;       else XB_SPIN(xb_ld(&bar[XB_TOPGEN]) == tg, bar);
;       __builtin_amdgcn_fence(__ATOMIC_ACQUIRE, "agent");
;       xb_add(&bar[XB_XGEN(b.x)], 1u);
;       asm volatile("s_waitcnt vmcnt(0)" ::: "memory");
;     } else {
;       XB_SPIN(xb_ld(&bar[XB_XGEN(b.x)]) == gen, bar);
;       __builtin_amdgcn_fence(__ATOMIC_ACQUIRE, "agent");
;       asm volatile("s_waitcnt vmcnt(0)" ::: "memory");
;     }
;   }
;   __syncthreads();
; }
.LBB0_175:
	s_or_b64 exec, exec, s[38:39]
	v_readlane_b32 s98, v240, 48
	s_add_i32 s98, s98, 1
	s_nop 0
	v_writelane_b32 v240, s98, 48
	v_readlane_b32 s64, v240, 45
	s_waitcnt lgkmcnt(0)
	s_barrier
	s_cmp_lg_u32 s64, 0
	s_cbranch_scc1 .LBB0_317

; __device__ __forceinline__ unsigned xb_ld(unsigned* p) { return __hip_atomic_load(p, __ATOMIC_RELAXED, __HIP_MEMORY_SCOPE_AGENT); }
; __device__ __forceinline__ unsigned xb_add(unsigned* p, unsigned v) { return __hip_atomic_fetch_add(p, v, __ATOMIC_RELAXED, __HIP_MEMORY_SCOPE_AGENT); }
; #define XB_SPIN(cond, bar) do { unsigned _sp = 0; while (cond) { __builtin_amdgcn_s_sleep(1); \
;     if ((++_sp & 255u) == 0u) { if (xb_ld(&(bar)[XB_TMO])) break; if (_sp > XB_SPIN_CAP) { atomicAdd(&(bar)[XB_TMO], 1u); break; } } } } while (0)
; __device__ __forceinline__ void xcd_barrier(const XcdBarrier& b) {
;   asm volatile("s_waitcnt vmcnt(0)" ::: "memory");
;   __syncthreads();
;   if (threadIdx.x == 0) {
;     unsigned* bar = b.bar;
;     __builtin_amdgcn_s_waitcnt(0);
;     unsigned nloc = b.st[0], nx = b.st[1];
;     if (nloc == 0u) { xcd_barrier_complete(bar, b.x, nloc, nx); b.st[0] = nloc; b.st[1] = nx; }
;     const unsigned old = xb_add(&bar[XB_XSUB(b.x)], 1u);
;     const unsigned gen = old / nloc;
;     if (old + 1u == (gen + 1u) * nloc) {
;       __builtin_amdgcn_fence(__ATOMIC_RELEASE, "agent");
;       asm volatile("s_waitcnt vmcnt(0)" ::: "memory");
;       const unsigned og = xb_add(&bar[XB_TOP], 1u);
;       const unsigned tg = og / nx;
;       if (og + 1u == (tg + 1u) * nx) xb_add(&bar[XB_TOPGEN], 1u);
;       else XB_SPIN(xb_ld(&bar[XB_TOPGEN]) == tg, bar);
;       __builtin_amdgcn_fence(__ATOMIC_ACQUIRE, "agent");
;       xb_add(&bar[XB_XGEN(b.x)], 1u);
;       asm volatile("s_waitcnt vmcnt(0)" ::: "memory");
;     } else {
;       XB_SPIN(xb_ld(&bar[XB_XGEN(b.x)]) == gen, bar);
;       __builtin_amdgcn_fence(__ATOMIC_ACQUIRE, "agent");
;       asm volatile("s_waitcnt vmcnt(0)" ::: "memory");
;     }
;   }
;   __syncthreads();
; }
.LBB0_316:
	s_or_b64 exec, exec, s[38:39]
	v_readlane_b32 s98, v240, 48
	s_add_i32 s98, s98, 1
	s_nop 0
	v_writelane_b32 v240, s98, 48
	s_waitcnt lgkmcnt(0)
	s_barrier

; __device__ __forceinline__ float softplusf_(float y) { return fmaxf(y, 0.f) + log1pf(__expf(-fabsf(y))); }
; __device__ __forceinline__ unsigned xb_ld(unsigned* p) { return __hip_atomic_load(p, __ATOMIC_RELAXED, __HIP_MEMORY_SCOPE_AGENT); }
; __device__ void ph_gdn_prep(const Params& p, int l, char* smem) {
;     ...
;   for (int task = gw; task < 2304; task += nw) {
;     const int chunk = task % 72, r = task / 72, dir = r & 1, h = (r >> 1) & 3, bl = r >> 3;
;     const int tk = lane & 31;
;     const float* gp = p.gates + (long)scan_row(bl, dir, chunk * 32 + tk) * GLD;
;     float ig = gp[32 + dir * 4 + h] + p.ml_i_bias[l * 8 + dir * 4 + h];
;     float F = -softplusf_(-(gp[40 + dir * 4 + h] + p.ml_f_bias[l * 8 + dir * 4 + h]));
; #pragma unroll
;     for (int o = 1; o < 32; o <<= 1) { float t2 = __shfl_up(F, o); if (tk >= o) F += t2; }
;     float a = ig - F;
;     float pm = a;
; #pragma unroll
;     for (int o = 1; o < 32; o <<= 1) { float t2 = __shfl_up(pm, o); if (tk >= o) pm = fmaxf(pm, t2); }
;     if (lane < 32) { float* o_ = p.mprep + (long)task * 96; o_[tk] = F; o_[32 + tk] = a; o_[64 + tk] = pm; }
; __device__ __forceinline__ void xcd_barrier(const XcdBarrier& b) {
;   asm volatile("s_waitcnt vmcnt(0)" ::: "memory");
;   __syncthreads();
;   if (threadIdx.x == 0) {
;     unsigned* bar = b.bar;
;     __builtin_amdgcn_s_waitcnt(0);
;     unsigned nloc = b.st[0], nx = b.st[1];
;     if (nloc == 0u) { xcd_barrier_complete(bar, b.x, nloc, nx); b.st[0] = nloc; b.st[1] = nx; }
;     const unsigned old = xb_add(&bar[XB_XSUB(b.x)], 1u);
;     const unsigned gen = old / nloc;
;     if (old + 1u == (gen + 1u) * nloc) {
;       __builtin_amdgcn_fence(__ATOMIC_RELEASE, "agent");
;       asm volatile("s_waitcnt vmcnt(0)" ::: "memory");
;       const unsigned og = xb_add(&bar[XB_TOP], 1u);
;       const unsigned tg = og / nx;
;       if (og + 1u == (tg + 1u) * nx) xb_add(&bar[XB_TOPGEN], 1u);
;       else XB_SPIN(xb_ld(&bar[XB_TOPGEN]) == tg, bar);
;       __builtin_amdgcn_fence(__ATOMIC_ACQUIRE, "agent");
;       xb_add(&bar[XB_XGEN(b.x)], 1u);
;       asm volatile("s_waitcnt vmcnt(0)" ::: "memory");
;     } else {
;       XB_SPIN(xb_ld(&bar[XB_XGEN(b.x)]) == gen, bar);
;       __builtin_amdgcn_fence(__ATOMIC_ACQUIRE, "agent");
;       asm volatile("s_waitcnt vmcnt(0)" ::: "memory");
;     }
;   }
;   __syncthreads();
; }
.LBB0_475:
	s_or_b64 exec, exec, s[38:39]
	v_readlane_b32 s98, v240, 48
	s_add_i32 s98, s98, 1
	s_nop 0
	v_writelane_b32 v240, s98, 48
	v_mov_b32_e32 v7, v156
	s_waitcnt lgkmcnt(0)
	s_barrier
	v_readlane_b32 s38, v241, 2
	v_ashrrev_i32_e32 v8, 6, v7
	s_movk_i32 s12, 0x900
	v_add_u32_e32 v79, s38, v8
	v_and_b32_e32 v6, 63, v7
	v_cmp_gt_i32_e32 vcc, s12, v79
	v_and_b32_e32 v78, 31, v7
	v_lshlrev_b32_e32 v5, 5, v8
	s_and_saveexec_b64 s[52:53], vcc
	s_cbranch_execz .LBB0_480
	v_readlane_b32 s12, v241, 30
	v_lshlrev_b32_e32 v0, 2, v78
	v_readlane_b32 s14, v241, 32
	v_readlane_b32 s15, v241, 33
	v_readlane_b32 s12, v241, 25
	v_cmp_gt_u32_e32 vcc, 32, v6
	v_lshl_add_u64 v[2:3], s[14:15], 0, v[0:1]
	v_add_u32_e32 v0, -1, v157
	v_cmp_lt_i32_e64 s[38:39], v0, v170
	v_add3_u32 v4, s12, v5, v78
	s_lshl_b32 s56, s58, 5
	v_cndmask_b32_e64 v0, v0, v157, s[38:39]
	v_lshlrev_b32_e32 v9, 2, v0
	v_add_u32_e32 v0, -2, v157
	v_cmp_lt_i32_e64 s[40:41], v0, v170
	v_cmp_eq_u32_e64 s[38:39], 0, v78
	v_sub_u32_e32 v14, 0, v4
	v_cndmask_b32_e64 v0, v0, v157, s[40:41]
	v_lshlrev_b32_e32 v10, 2, v0
	v_add_u32_e32 v0, -4, v157
	v_cmp_lt_i32_e64 s[42:43], v0, v170
	v_cmp_gt_u32_e64 s[40:41], 2, v78
	s_mov_b64 s[54:55], 0
	v_cndmask_b32_e64 v0, v0, v157, s[42:43]
	v_lshlrev_b32_e32 v11, 2, v0
	v_add_u32_e32 v0, -8, v157
	v_cmp_lt_i32_e64 s[44:45], v0, v170
	v_cmp_gt_u32_e64 s[42:43], 4, v78
	v_mov_b32_e32 v15, v79
	v_cndmask_b32_e64 v0, v0, v157, s[44:45]
	v_lshlrev_b32_e32 v12, 2, v0
	v_add_u32_e32 v0, -16, v157
	v_cmp_lt_i32_e64 s[46:47], v0, v170
	v_cmp_gt_u32_e64 s[44:45], 8, v78
	v_readlane_b32 s13, v241, 31
	v_cndmask_b32_e64 v0, v0, v157, s[46:47]
	v_lshlrev_b32_e32 v13, 2, v0
	v_cmp_gt_u32_e64 s[46:47], 16, v78
	s_branch .LBB0_478

; __device__ __forceinline__ unsigned xb_ld(unsigned* p) { return __hip_atomic_load(p, __ATOMIC_RELAXED, __HIP_MEMORY_SCOPE_AGENT); }
; __device__ __forceinline__ unsigned xb_add(unsigned* p, unsigned v) { return __hip_atomic_fetch_add(p, v, __ATOMIC_RELAXED, __HIP_MEMORY_SCOPE_AGENT); }
; #define XB_SPIN(cond, bar) do { unsigned _sp = 0; while (cond) { __builtin_amdgcn_s_sleep(1); \
;     if ((++_sp & 255u) == 0u) { if (xb_ld(&(bar)[XB_TMO])) break; if (_sp > XB_SPIN_CAP) { atomicAdd(&(bar)[XB_TMO], 1u); break; } } } } while (0)
; __device__ void ph_scan(const Params& p, int l, int g, char* smem) {
;   const int b = blockIdx.x;
;   __shared__ int tb_s[2];
;   int u0, ustep;
;   if (gridDim.x == 512) {
;     ustep = 512;
;     u0 = b < 128 ? 128 + b : (b < 256 ? b - 128 : (b < 384 ? b : 384));
;   } else { u0 = b; ustep = gridDim.x; }
;   for (int u = u0; u < 384; u += ustep) scan_unit_mma(p, l, g, u, *(CSmem*)smem);
; __device__ __forceinline__ void xcd_barrier(const XcdBarrier& b) {
;   asm volatile("s_waitcnt vmcnt(0)" ::: "memory");
;   __syncthreads();
;   if (threadIdx.x == 0) {
;     unsigned* bar = b.bar;
;     __builtin_amdgcn_s_waitcnt(0);
;     unsigned nloc = b.st[0], nx = b.st[1];
;     if (nloc == 0u) { xcd_barrier_complete(bar, b.x, nloc, nx); b.st[0] = nloc; b.st[1] = nx; }
;     const unsigned old = xb_add(&bar[XB_XSUB(b.x)], 1u);
;     const unsigned gen = old / nloc;
;     if (old + 1u == (gen + 1u) * nloc) {
;       __builtin_amdgcn_fence(__ATOMIC_RELEASE, "agent");
;       asm volatile("s_waitcnt vmcnt(0)" ::: "memory");
;       const unsigned og = xb_add(&bar[XB_TOP], 1u);
;       const unsigned tg = og / nx;
;       if (og + 1u == (tg + 1u) * nx) xb_add(&bar[XB_TOPGEN], 1u);
;       else XB_SPIN(xb_ld(&bar[XB_TOPGEN]) == tg, bar);
;       __builtin_amdgcn_fence(__ATOMIC_ACQUIRE, "agent");
;       xb_add(&bar[XB_XGEN(b.x)], 1u);
;       asm volatile("s_waitcnt vmcnt(0)" ::: "memory");
;     } else {
;       XB_SPIN(xb_ld(&bar[XB_XGEN(b.x)]) == gen, bar);
;       __builtin_amdgcn_fence(__ATOMIC_ACQUIRE, "agent");
;       asm volatile("s_waitcnt vmcnt(0)" ::: "memory");
;     }
;   }
;   __syncthreads();
; }
.LBB0_609:
	s_or_b64 exec, exec, s[38:39]
	v_readlane_b32 s98, v240, 48
	s_add_i32 s98, s98, 1
	s_nop 0
	v_writelane_b32 v240, s98, 48
	v_readlane_b32 s12, v241, 23
	v_readlane_b32 s13, v241, 24
	s_andn2_b64 vcc, exec, s[12:13]
	v_readlane_b32 s70, v241, 22
	s_waitcnt lgkmcnt(0)
	s_barrier
	s_cbranch_vccz .LBB0_612

; __device__ __forceinline__ int otid() { int t = threadIdx.x; asm volatile("" : "+v"(t)); return t; }
; __device__ __forceinline__ unsigned xb_ld(unsigned* p) { return __hip_atomic_load(p, __ATOMIC_RELAXED, __HIP_MEMORY_SCOPE_AGENT); }
; __device__ __forceinline__ unsigned xb_add(unsigned* p, unsigned v) { return __hip_atomic_fetch_add(p, v, __ATOMIC_RELAXED, __HIP_MEMORY_SCOPE_AGENT); }
; #define XB_SPIN(cond, bar) do { unsigned _sp = 0; while (cond) { __builtin_amdgcn_s_sleep(1); \
;     if ((++_sp & 255u) == 0u) { if (xb_ld(&(bar)[XB_TMO])) break; if (_sp > XB_SPIN_CAP) { atomicAdd(&(bar)[XB_TMO], 1u); break; } } } } while (0)
; __device__ void ph_brfin(const Params& p, int l, int g) {
;   const int tid = otid();
;   const int lane = tid & 63;
;   const int gw = blockIdx.x * 4 + (tid >> 6), nw = gridDim.x * 4;
;   uint4 na0, na1, nb0, nb1, nz0, nz1, ng0, ng1;
;   float4 no0, no1, no2, no3;
;   const uint4 zz = uint4{0u, 0u, 0u, 0u};
;   na0 = na1 = nb0 = nb1 = nz0 = nz1 = ng0 = ng1 = zz;
;   no0 = no1 = no2 = no3 = float4{0.f, 0.f, 0.f, 0.f};
;     ...
;   BR_LOAD(gw)
; __device__ __forceinline__ void xcd_barrier(const XcdBarrier& b) {
;   asm volatile("s_waitcnt vmcnt(0)" ::: "memory");
;   __syncthreads();
;   if (threadIdx.x == 0) {
;     unsigned* bar = b.bar;
;     __builtin_amdgcn_s_waitcnt(0);
;     unsigned nloc = b.st[0], nx = b.st[1];
;     if (nloc == 0u) { xcd_barrier_complete(bar, b.x, nloc, nx); b.st[0] = nloc; b.st[1] = nx; }
;     const unsigned old = xb_add(&bar[XB_XSUB(b.x)], 1u);
;     const unsigned gen = old / nloc;
;     if (old + 1u == (gen + 1u) * nloc) {
;       __builtin_amdgcn_fence(__ATOMIC_RELEASE, "agent");
;       asm volatile("s_waitcnt vmcnt(0)" ::: "memory");
;       const unsigned og = xb_add(&bar[XB_TOP], 1u);
;       const unsigned tg = og / nx;
;       if (og + 1u == (tg + 1u) * nx) xb_add(&bar[XB_TOPGEN], 1u);
;       else XB_SPIN(xb_ld(&bar[XB_TOPGEN]) == tg, bar);
;       __builtin_amdgcn_fence(__ATOMIC_ACQUIRE, "agent");
;       xb_add(&bar[XB_XGEN(b.x)], 1u);
;       asm volatile("s_waitcnt vmcnt(0)" ::: "memory");
;     } else {
;       XB_SPIN(xb_ld(&bar[XB_XGEN(b.x)]) == gen, bar);
;       __builtin_amdgcn_fence(__ATOMIC_ACQUIRE, "agent");
;       asm volatile("s_waitcnt vmcnt(0)" ::: "memory");
;     }
;   }
;   __syncthreads();
; }
.LBB0_899:
	s_or_b64 exec, exec, s[38:39]
	v_readlane_b32 s98, v240, 48
	s_add_i32 s98, s98, 1
	s_nop 0
	v_writelane_b32 v240, s98, 48
	v_mov_b32_e32 v0, v156
	s_waitcnt lgkmcnt(0)
	s_barrier
	v_readlane_b32 s38, v241, 2
	v_ashrrev_i32_e32 v16, 6, v0
	s_movk_i32 s12, 0x6c00
	v_add_u32_e32 v108, s38, v16
	v_cmp_gt_i32_e32 vcc, s12, v108
	s_and_saveexec_b64 s[44:45], vcc
	s_cbranch_execz .LBB0_920
	v_and_b32_e32 v17, 63, v0
	v_mul_hi_i32 v0, v108, s59
	v_lshrrev_b32_e32 v2, 31, v0
	v_ashrrev_i32_e32 v0, 11, v0
	v_add_u32_e32 v18, v0, v2
	v_mul_i32_i24_e32 v0, 0x2400, v18
	v_sub_u32_e32 v14, v108, v0
	v_mul_i32_i24_e32 v0, 0xe39, v14
	v_lshrrev_b32_e32 v2, 31, v0
	v_lshrrev_b32_e32 v0, 23, v0
	v_add_u16_e32 v0, v0, v2
	v_mul_lo_u16_e32 v0, 0x900, v0
	v_readlane_b32 s12, v240, 2
	v_sub_u16_e32 v0, v14, v0
	v_readlane_b32 s13, v240, 3
	v_cmp_lt_i16_e32 vcc, s24, v0
	s_xor_b64 s[46:47], s[12:13], -1
	s_or_b64 s[38:39], s[46:47], vcc
	v_lshlrev_b32_e32 v0, 4, v17
	s_and_saveexec_b64 s[40:41], s[38:39]
	s_xor_b64 s[42:43], exec, s[40:41]
	s_cbranch_execz .LBB0_904
	v_mov_b64_e32 v[2:3], s[88:89]
	v_lshlrev_b32_e32 v4, 10, v18
	v_mad_i64_i32 v[2:3], s[38:39], v14, s26, v[2:3]
	v_ashrrev_i32_e32 v5, 31, v4
	v_lshl_add_u64 v[2:3], v[4:5], 1, v[2:3]
	v_lshlrev_b32_e32 v4, 5, v17
	v_mov_b32_e32 v5, v1
	v_lshl_add_u64 v[2:3], v[2:3], 0, v[4:5]
	s_mov_b64 s[12:13], 0x3600000
	v_lshl_add_u64 v[6:7], v[2:3], 0, s[12:13]
	global_load_dwordx4 v[82:85], v[2:3], off offset:16
	global_load_dwordx4 v[90:93], v[2:3], off
	v_add_co_u32_e32 v2, vcc, 0x3600000, v2
	s_movk_i32 s12, 0x2400
	s_nop 0
	v_addc_co_u32_e32 v3, vcc, 0, v3, vcc
	global_load_dwordx4 v[94:97], v[2:3], off
	global_load_dwordx4 v[86:89], v[6:7], off offset:16
	v_add_u32_e32 v2, 0xffffdc00, v108
	v_ashrrev_i32_e32 v15, 31, v14
	v_add_u32_e32 v6, 0x23ff, v108
	v_cmp_gt_u32_e64 s[38:39], s12, v2
	s_movk_i32 s10, 0x47ff
	v_lshlrev_b64 v[2:3], 15, v[14:15]
	v_cndmask_b32_e64 v7, v181, v182, s[38:39]
	v_cmp_gt_u32_e64 s[40:41], s10, v6
	v_lshl_add_u64 v[14:15], s[86:87], 0, v[2:3]
	v_mov_b32_e32 v3, v1
	v_cndmask_b32_e64 v2, v7, v183, s[40:41]
	v_lshlrev_b32_e32 v2, 1, v2
	v_lshl_add_u64 v[2:3], v[14:15], 0, v[2:3]
	v_lshl_add_u64 v[2:3], v[2:3], 0, v[4:5]
	global_load_dwordx4 v[10:13], v[2:3], off offset:16
	global_load_dwordx4 v[70:73], v[2:3], off
	v_mov_b32_e32 v4, v1
	v_mov_b32_e32 v2, v1
	v_mov_b32_e32 v3, v1
	v_mov_b64_e32 v[8:9], v[4:5]
	v_cmp_lt_i32_e32 vcc, s10, v108
	v_mov_b64_e32 v[6:7], v[2:3]
	s_and_saveexec_b64 s[48:49], vcc
	s_cbranch_execz .LBB0_903
	v_lshlrev_b32_e32 v2, 1, v0
	v_mov_b32_e32 v3, v1
	v_lshl_add_u64 v[2:3], v[14:15], 0, v[2:3]
	s_mov_b64 s[12:13], 0x5800
	v_lshl_add_u64 v[4:5], v[2:3], 0, s[12:13]
	v_add_co_u32_e32 v2, vcc, 0x5000, v2
	s_nop 1
	v_addc_co_u32_e32 v3, vcc, 0, v3, vcc
	global_load_dwordx4 v[6:9], v[2:3], off offset:2048
	s_nop 0
	global_load_dwordx4 v[2:5], v[4:5], off offset:16

; __device__ __forceinline__ unsigned xb_ld(unsigned* p) { return __hip_atomic_load(p, __ATOMIC_RELAXED, __HIP_MEMORY_SCOPE_AGENT); }
; __device__ __forceinline__ unsigned xb_add(unsigned* p, unsigned v) { return __hip_atomic_fetch_add(p, v, __ATOMIC_RELAXED, __HIP_MEMORY_SCOPE_AGENT); }
; #define XB_SPIN(cond, bar) do { unsigned _sp = 0; while (cond) { __builtin_amdgcn_s_sleep(1); \
;     if ((++_sp & 255u) == 0u) { if (xb_ld(&(bar)[XB_TMO])) break; if (_sp > XB_SPIN_CAP) { atomicAdd(&(bar)[XB_TMO], 1u); break; } } } } while (0)
; __device__ __forceinline__ void xcd_barrier(const XcdBarrier& b) {
;   asm volatile("s_waitcnt vmcnt(0)" ::: "memory");
;   __syncthreads();
;   if (threadIdx.x == 0) {
;     unsigned* bar = b.bar;
;     __builtin_amdgcn_s_waitcnt(0);
;     unsigned nloc = b.st[0], nx = b.st[1];
;     if (nloc == 0u) { xcd_barrier_complete(bar, b.x, nloc, nx); b.st[0] = nloc; b.st[1] = nx; }
;     const unsigned old = xb_add(&bar[XB_XSUB(b.x)], 1u);
;     const unsigned gen = old / nloc;
;     if (old + 1u == (gen + 1u) * nloc) {
;       __builtin_amdgcn_fence(__ATOMIC_RELEASE, "agent");
;       asm volatile("s_waitcnt vmcnt(0)" ::: "memory");
;       const unsigned og = xb_add(&bar[XB_TOP], 1u);
;       const unsigned tg = og / nx;
;       if (og + 1u == (tg + 1u) * nx) xb_add(&bar[XB_TOPGEN], 1u);
;       else XB_SPIN(xb_ld(&bar[XB_TOPGEN]) == tg, bar);
;       __builtin_amdgcn_fence(__ATOMIC_ACQUIRE, "agent");
;       xb_add(&bar[XB_XGEN(b.x)], 1u);
;       asm volatile("s_waitcnt vmcnt(0)" ::: "memory");
;     } else {
;       XB_SPIN(xb_ld(&bar[XB_XGEN(b.x)]) == gen, bar);
;       __builtin_amdgcn_fence(__ATOMIC_ACQUIRE, "agent");
;       asm volatile("s_waitcnt vmcnt(0)" ::: "memory");
;     }
;   }
;   __syncthreads();
; }
.LBB0_956:
	s_waitcnt lgkmcnt(0)
	v_readlane_b32 s42, v242, 58
	v_readlane_b32 s43, v242, 59
	v_mov_b32_e32 v4, 1
	v_readlane_b32 s46, v240, 48
	s_add_i32 s46, s46, 1
	v_mul_lo_u32 v6, v3, s46
	v_mul_lo_u32 v5, v2, s46
	s_nop 1
	global_atomic_add v4, v1, v4, s[42:43] sc0
	v_readlane_b32 s44, v242, 62
	v_readlane_b32 s45, v242, 63
	s_waitcnt vmcnt(0)
	v_add_u32_e32 v4, 1, v4
	v_cmp_eq_u32_e32 vcc, v4, v6
	s_cbranch_vccz .Lgb6_poll
	buffer_wbl2 sc1
	s_waitcnt vmcnt(0) lgkmcnt(0)
	v_mov_b32_e32 v4, 1
	global_atomic_add v1, v4, s[44:45]
.Lgb6_poll:
	s_movk_i32 s46, 0x2000
.Lgb6_spin:
	global_load_dword v4, v1, s[44:45] sc1
	s_waitcnt vmcnt(0)
	v_cmp_ge_u32_e32 vcc, v4, v5
	s_cbranch_vccnz .Lgb6_done
	s_sleep 1
	s_sub_u32 s46, s46, 1
	s_cmp_lg_u32 s46, 0
	s_cbranch_scc1 .Lgb6_spin

; __device__ __forceinline__ unsigned xb_ld(unsigned* p) { return __hip_atomic_load(p, __ATOMIC_RELAXED, __HIP_MEMORY_SCOPE_AGENT); }
; __device__ __forceinline__ unsigned xb_add(unsigned* p, unsigned v) { return __hip_atomic_fetch_add(p, v, __ATOMIC_RELAXED, __HIP_MEMORY_SCOPE_AGENT); }
; #define XB_SPIN(cond, bar) do { unsigned _sp = 0; while (cond) { __builtin_amdgcn_s_sleep(1); \
;     if ((++_sp & 255u) == 0u) { if (xb_ld(&(bar)[XB_TMO])) break; if (_sp > XB_SPIN_CAP) { atomicAdd(&(bar)[XB_TMO], 1u); break; } } } } while (0)
; __device__ void ph_gemm_merge(const Params& p, int l, char* smem) {
;   for (int t = blockIdx.x; t < 72 * 8; t += gridDim.x) {
;     int nt = t / 72, mt = t % 72;
;     if (l == 1 && (mt % 18) < 2) continue;
; __device__ __forceinline__ void xcd_barrier(const XcdBarrier& b) {
;   asm volatile("s_waitcnt vmcnt(0)" ::: "memory");
;   __syncthreads();
;   if (threadIdx.x == 0) {
;     unsigned* bar = b.bar;
;     __builtin_amdgcn_s_waitcnt(0);
;     unsigned nloc = b.st[0], nx = b.st[1];
;     if (nloc == 0u) { xcd_barrier_complete(bar, b.x, nloc, nx); b.st[0] = nloc; b.st[1] = nx; }
;     const unsigned old = xb_add(&bar[XB_XSUB(b.x)], 1u);
;     const unsigned gen = old / nloc;
;     if (old + 1u == (gen + 1u) * nloc) {
;       __builtin_amdgcn_fence(__ATOMIC_RELEASE, "agent");
;       asm volatile("s_waitcnt vmcnt(0)" ::: "memory");
;       const unsigned og = xb_add(&bar[XB_TOP], 1u);
;       const unsigned tg = og / nx;
;       if (og + 1u == (tg + 1u) * nx) xb_add(&bar[XB_TOPGEN], 1u);
;       else XB_SPIN(xb_ld(&bar[XB_TOPGEN]) == tg, bar);
;       __builtin_amdgcn_fence(__ATOMIC_ACQUIRE, "agent");
;       xb_add(&bar[XB_XGEN(b.x)], 1u);
;       asm volatile("s_waitcnt vmcnt(0)" ::: "memory");
;     } else {
;       XB_SPIN(xb_ld(&bar[XB_XGEN(b.x)]) == gen, bar);
;       __builtin_amdgcn_fence(__ATOMIC_ACQUIRE, "agent");
;       asm volatile("s_waitcnt vmcnt(0)" ::: "memory");
;     }
;   }
;   __syncthreads();
; }
.LBB0_992:
	s_or_b64 exec, exec, s[40:41]
	v_readlane_b32 s98, v240, 48
	s_add_i32 s98, s98, 1
	s_nop 0
	v_writelane_b32 v240, s98, 48
	v_readlane_b32 s12, v241, 15
	v_readlane_b32 s13, v241, 16
	s_andn2_b64 vcc, exec, s[12:13]
	s_waitcnt lgkmcnt(0)
	s_barrier
	s_cbranch_vccnz .LBB0_1001
	v_readlane_b32 s65, v242, 2
	s_branch .LBB0_995

; __device__ __forceinline__ unsigned xb_ld(unsigned* p) { return __hip_atomic_load(p, __ATOMIC_RELAXED, __HIP_MEMORY_SCOPE_AGENT); }
; __device__ __forceinline__ unsigned xb_add(unsigned* p, unsigned v) { return __hip_atomic_fetch_add(p, v, __ATOMIC_RELAXED, __HIP_MEMORY_SCOPE_AGENT); }
; #define XB_SPIN(cond, bar) do { unsigned _sp = 0; while (cond) { __builtin_amdgcn_s_sleep(1); \
;     if ((++_sp & 255u) == 0u) { if (xb_ld(&(bar)[XB_TMO])) break; if (_sp > XB_SPIN_CAP) { atomicAdd(&(bar)[XB_TMO], 1u); break; } } } } while (0)
; __device__ void ph_gemm_out(const Params& p, int l, int g, char* smem) {
;   for (int t = (int)gridDim.x - 1 - (int)blockIdx.x; t < 72 * 8; t += gridDim.x) {
;     int nt = t / 72, mt = t % 72;
;     if (l == 1 && (mt % 18) < 2) continue;
; __device__ __forceinline__ void xcd_barrier(const XcdBarrier& b) {
;   asm volatile("s_waitcnt vmcnt(0)" ::: "memory");
;   __syncthreads();
;   if (threadIdx.x == 0) {
;     unsigned* bar = b.bar;
;     __builtin_amdgcn_s_waitcnt(0);
;     unsigned nloc = b.st[0], nx = b.st[1];
;     if (nloc == 0u) { xcd_barrier_complete(bar, b.x, nloc, nx); b.st[0] = nloc; b.st[1] = nx; }
;     const unsigned old = xb_add(&bar[XB_XSUB(b.x)], 1u);
;     const unsigned gen = old / nloc;
;     if (old + 1u == (gen + 1u) * nloc) {
;       __builtin_amdgcn_fence(__ATOMIC_RELEASE, "agent");
;       asm volatile("s_waitcnt vmcnt(0)" ::: "memory");
;       const unsigned og = xb_add(&bar[XB_TOP], 1u);
;       const unsigned tg = og / nx;
;       if (og + 1u == (tg + 1u) * nx) xb_add(&bar[XB_TOPGEN], 1u);
;       else XB_SPIN(xb_ld(&bar[XB_TOPGEN]) == tg, bar);
;       __builtin_amdgcn_fence(__ATOMIC_ACQUIRE, "agent");
;       xb_add(&bar[XB_XGEN(b.x)], 1u);
;       asm volatile("s_waitcnt vmcnt(0)" ::: "memory");
;     } else {
;       XB_SPIN(xb_ld(&bar[XB_XGEN(b.x)]) == gen, bar);
;       __builtin_amdgcn_fence(__ATOMIC_ACQUIRE, "agent");
;       asm volatile("s_waitcnt vmcnt(0)" ::: "memory");
;     }
;   }
;   __syncthreads();
; }
.LBB0_1053:
	s_or_b64 exec, exec, s[40:41]
	v_readlane_b32 s98, v240, 48
	s_add_i32 s98, s98, 1
	s_nop 0
	v_writelane_b32 v240, s98, 48
	v_readlane_b32 s12, v241, 20
	v_readlane_b32 s13, v241, 21
	s_andn2_b64 vcc, exec, s[12:13]
	s_waitcnt lgkmcnt(0)
	s_barrier
	s_cbranch_vccnz .LBB0_1076
	v_readlane_b32 s10, v240, 45
	s_lshl_b32 s44, s10, 2
	v_readlane_b32 s45, v241, 19
	s_branch .LBB0_1057

; __device__ __forceinline__ unsigned xb_ld(unsigned* p) { return __hip_atomic_load(p, __ATOMIC_RELAXED, __HIP_MEMORY_SCOPE_AGENT); }
; __device__ __forceinline__ unsigned xb_add(unsigned* p, unsigned v) { return __hip_atomic_fetch_add(p, v, __ATOMIC_RELAXED, __HIP_MEMORY_SCOPE_AGENT); }
; #define XB_SPIN(cond, bar) do { unsigned _sp = 0; while (cond) { __builtin_amdgcn_s_sleep(1); \
;     if ((++_sp & 255u) == 0u) { if (xb_ld(&(bar)[XB_TMO])) break; if (_sp > XB_SPIN_CAP) { atomicAdd(&(bar)[XB_TMO], 1u); break; } } } } while (0)
; __device__ __forceinline__ void xcd_barrier(const XcdBarrier& b) {
;   asm volatile("s_waitcnt vmcnt(0)" ::: "memory");
;   __syncthreads();
;   if (threadIdx.x == 0) {
;     unsigned* bar = b.bar;
;     __builtin_amdgcn_s_waitcnt(0);
;     unsigned nloc = b.st[0], nx = b.st[1];
;     if (nloc == 0u) { xcd_barrier_complete(bar, b.x, nloc, nx); b.st[0] = nloc; b.st[1] = nx; }
;     const unsigned old = xb_add(&bar[XB_XSUB(b.x)], 1u);
;     const unsigned gen = old / nloc;
;     if (old + 1u == (gen + 1u) * nloc) {
;       __builtin_amdgcn_fence(__ATOMIC_RELEASE, "agent");
;       asm volatile("s_waitcnt vmcnt(0)" ::: "memory");
;       const unsigned og = xb_add(&bar[XB_TOP], 1u);
;       const unsigned tg = og / nx;
;       if (og + 1u == (tg + 1u) * nx) xb_add(&bar[XB_TOPGEN], 1u);
;       else XB_SPIN(xb_ld(&bar[XB_TOPGEN]) == tg, bar);
;       __builtin_amdgcn_fence(__ATOMIC_ACQUIRE, "agent");
;       xb_add(&bar[XB_XGEN(b.x)], 1u);
;       asm volatile("s_waitcnt vmcnt(0)" ::: "memory");
;     } else {
;       XB_SPIN(xb_ld(&bar[XB_XGEN(b.x)]) == gen, bar);
;       __builtin_amdgcn_fence(__ATOMIC_ACQUIRE, "agent");
;       asm volatile("s_waitcnt vmcnt(0)" ::: "memory");
;     }
;   }
;   __syncthreads();
; }
.LBB0_1180:
	s_waitcnt lgkmcnt(0)
	v_readlane_b32 s40, v242, 58
	v_readlane_b32 s41, v242, 59
	v_mov_b32_e32 v4, 1
	v_readlane_b32 s46, v240, 48
	s_add_i32 s46, s46, 1
	v_mul_lo_u32 v6, v3, s46
	v_mul_lo_u32 v5, v2, s46
	s_nop 1
	global_atomic_add v4, v1, v4, s[40:41] sc0
	v_readlane_b32 s44, v242, 62
	v_readlane_b32 s45, v242, 63
	s_waitcnt vmcnt(0)
	v_add_u32_e32 v4, 1, v4
	v_cmp_eq_u32_e32 vcc, v4, v6
	s_cbranch_vccz .Lgb8_poll
	buffer_wbl2 sc1
	s_waitcnt vmcnt(0) lgkmcnt(0)
	v_mov_b32_e32 v4, 1
	global_atomic_add v1, v4, s[44:45]

; __device__ __forceinline__ unsigned xb_ld(unsigned* p) { return __hip_atomic_load(p, __ATOMIC_RELAXED, __HIP_MEMORY_SCOPE_AGENT); }
; __device__ __forceinline__ unsigned xb_add(unsigned* p, unsigned v) { return __hip_atomic_fetch_add(p, v, __ATOMIC_RELAXED, __HIP_MEMORY_SCOPE_AGENT); }
; #define XB_SPIN(cond, bar) do { unsigned _sp = 0; while (cond) { __builtin_amdgcn_s_sleep(1); \
;     if ((++_sp & 255u) == 0u) { if (xb_ld(&(bar)[XB_TMO])) break; if (_sp > XB_SPIN_CAP) { atomicAdd(&(bar)[XB_TMO], 1u); break; } } } } while (0)
; __device__ __forceinline__ void xcd_barrier(const XcdBarrier& b) {
;   asm volatile("s_waitcnt vmcnt(0)" ::: "memory");
;   __syncthreads();
;   if (threadIdx.x == 0) {
;     unsigned* bar = b.bar;
;     __builtin_amdgcn_s_waitcnt(0);
;     unsigned nloc = b.st[0], nx = b.st[1];
;     if (nloc == 0u) { xcd_barrier_complete(bar, b.x, nloc, nx); b.st[0] = nloc; b.st[1] = nx; }
;     const unsigned old = xb_add(&bar[XB_XSUB(b.x)], 1u);
;     const unsigned gen = old / nloc;
;     if (old + 1u == (gen + 1u) * nloc) {
;       __builtin_amdgcn_fence(__ATOMIC_RELEASE, "agent");
;       asm volatile("s_waitcnt vmcnt(0)" ::: "memory");
;       const unsigned og = xb_add(&bar[XB_TOP], 1u);
;       const unsigned tg = og / nx;
;       if (og + 1u == (tg + 1u) * nx) xb_add(&bar[XB_TOPGEN], 1u);
;       else XB_SPIN(xb_ld(&bar[XB_TOPGEN]) == tg, bar);
;       __builtin_amdgcn_fence(__ATOMIC_ACQUIRE, "agent");
;       xb_add(&bar[XB_XGEN(b.x)], 1u);
;       asm volatile("s_waitcnt vmcnt(0)" ::: "memory");
;     } else {
;       XB_SPIN(xb_ld(&bar[XB_XGEN(b.x)]) == gen, bar);
;       __builtin_amdgcn_fence(__ATOMIC_ACQUIRE, "agent");
;       asm volatile("s_waitcnt vmcnt(0)" ::: "memory");
;     }
;   }
;   __syncthreads();
; }
.Lgb8_done:
	buffer_inv sc1
	s_waitcnt vmcnt(0)
	s_mov_b64 s[42:43], 0
	s_getpc_b64 s[98:99]
